# v8 (P5 epilogue prefetch) + P6 K-loop DMA saddr form
# baseline (speedup 1.0000x reference)
; #define PG8_STAGE(bufoff, gbase, voff) do { _Pragma("unroll") for (int _i = 0; _i < 2; ++_i) \
;         __builtin_amdgcn_global_load_lds((const unsigned*)((const char*)(gbase) + (voff)[_i]), (LAS unsigned*)(lds + (bufoff) + ldsw + _i * 8192), 16, 0, 0); } while (0)
; #define PG8_WAIT_V(n) asm volatile("s_waitcnt vmcnt(" #n ")" ::: "memory")
; template <class Epi, bool ALIGN_EPI, bool SPLITA>
; __device__ __forceinline__ void gemm_phase(LAS unsigned char* lds, const Gemm g, const StaticOrder& S, const Epi& E) {
;     ...
;         for (int t = 0; t < nt; t += 2) {
;             const bool last = (t == nt - 2);
;             if constexpr (Epi::MIDK) { if (t == g.ksplit) E.mid(acc, cur, wr, wc, fr, fq); }
;             const char *a1, *a2;
;             if constexpr (SPLITA) {
;                 a1 = (t + 1 < g.ksplit) ? cA + (size_t)(t + 1) * kstep : cA2 + (size_t)(t + 1 - g.ksplit) * 2048;
;                 a2 = last ? nA : ((t + 2 < g.ksplit) ? cA + (size_t)(t + 2) * kstep : cA2 + (size_t)(t + 2 - g.ksplit) * 2048);
;             } else { a1 = cA + kofs(t + 1); a2 = last ? nA : cA + kofs(t + 2); }
;             const char* b2 = last ? nB : cB + (size_t)(t + 2) * kstepB;
;             const bool s2a = SPLITA && (t + 1 >= g.ksplit), s2b = SPLITA && !last && (t + 2 >= g.ksplit);
;             const char* a3 = a2 + ((Epi::KSUB || s2b) ? (size_t)2048 : kstep); const char* b3 = b2 + kstepB;
;             const bool m1 = SPLITA && mirC && (t + 1 < g.ksplit), m2 = SPLITA && (last ? mirN : (mirC && (t + 2 < g.ksplit)));
;             const unsigned vo1[2] = {s2a ? voffA2[0] : m1 ? voffAm[0] : voffA[0], s2a ? voffA2[1] : m1 ? voffAm[1] : voffA[1]}, vo2[2] = {s2b ? voffA2[0] : m2 ? voffAm[0] : voffA[0], s2b ? voffA2[1] : m2 ? voffAm[1] : voffA[1]};
;             const char* a1h = m1 ? a1 - hstepA : a1 + hstepA; const char* a2h = m2 ? a2 - hstepA : a2 + hstepA;
;             PG8_LDB(B0, 0, 0); PG8_LDB(B1, 0, 1); PG8_SCHED; PG8_LDA(At, 0, 0); PG8_STAGE(PG8_SA(1, 1), a1h, vo1);
;             PG8_WAIT_V(8); PG8_WAIT_L(0); PG8_BAR; PG8_MMA(0, 0, At, B0); PG8_MMA(0, 1, At, B1); PG8_BAR; PG8_SCHED;
;             PG8_LDA(At, 0, 1); PG8_STAGE(PG8_SB(0, 0), b2, voffB); PG8_STAGE(PG8_SB(0, 1), b2 + hstepB, voffB); PG8_STAGE(PG8_SA(0, 0), a2, vo2);
;             PG8_WAIT_V(8); PG8_WAIT_L(0); PG8_BAR; PG8_MMA(1, 0, At, B0); PG8_MMA(1, 1, At, B1); PG8_BAR; PG8_SCHED;
.LBB0_867:
	s_add_i32 s53, s28, 2
	s_lshr_b32 s2, s53, 2
	s_lshl_b64 s[12:13], s[2:3], 17
	s_add_i32 s2, s52, 0xfffff000
	s_and_b32 s2, s2, 0x1000
	s_add_u32 s12, s26, s12
	s_addc_u32 s13, s27, s13
	s_add_u32 s29, s12, s2
	s_addc_u32 s30, s13, 0
	s_add_i32 s2, s28, 4
	ds_read_b128 v[140:143], v151
	ds_read_b128 v[144:147], v151 offset:1024
	ds_read_b128 v[154:157], v151 offset:2048
	ds_read_b128 v[158:161], v151 offset:3072
	ds_read_b128 v[162:165], v152
	ds_read_b128 v[166:169], v152 offset:1024
	ds_read_b128 v[170:173], v152 offset:2048
	ds_read_b128 v[174:177], v152 offset:3072
	s_lshr_b32 s2, s2, 2
	s_lshl_b64 s[12:13], s[2:3], 17
	s_and_b32 s2, s52, 0x1000
	s_add_u32 s12, s26, s12
	s_addc_u32 s13, s27, s13
	s_add_u32 s2, s12, s2
	s_addc_u32 s31, s13, 0
	s_add_u32 s12, s29, 0x10800
	s_addc_u32 s13, s30, 0
	s_cmp_eq_u32 s28, 60
	s_cselect_b32 s28, s49, s50
	s_cselect_b32 s31, s17, s31
	s_cselect_b32 s30, s48, s2
	s_cselect_b32 s29, s19, s51
	s_add_i32 m0, s25, 0xc000
	ds_read_b128 v[178:181], v153
	ds_read_b128 v[182:185], v153 offset:1024
	ds_read_b128 v[186:189], v153 offset:2048
	ds_read_b128 v[190:193], v153 offset:3072
	ds_read_b128 v[194:197], v153 offset:4096
	ds_read_b128 v[198:201], v153 offset:5120
	ds_read_b128 v[202:205], v153 offset:6144
	ds_read_b128 v[206:209], v153 offset:7168
	global_load_lds_dwordx4 v134, s[12:13]
	s_add_i32 m0, s25, 0xe000
	s_nop 0
	global_load_lds_dwordx4 v130, s[12:13]
	s_waitcnt vmcnt(8)
	s_waitcnt lgkmcnt(0)
	s_barrier
	s_setprio 1
	s_waitcnt lgkmcnt(0)
	v_mfma_f32_16x16x32_bf16 v[124:127], v[140:143], v[178:181], v[124:127]
	v_mfma_f32_16x16x32_bf16 v[120:123], v[154:157], v[178:181], v[120:123]
	v_mfma_f32_16x16x32_bf16 v[108:111], v[140:143], v[186:189], v[108:111]
	v_mfma_f32_16x16x32_bf16 v[104:107], v[154:157], v[186:189], v[104:107]
	v_mfma_f32_16x16x32_bf16 v[96:99], v[140:143], v[194:197], v[96:99]
	v_mfma_f32_16x16x32_bf16 v[88:91], v[154:157], v[194:197], v[88:91]
	v_mfma_f32_16x16x32_bf16 v[80:83], v[140:143], v[202:205], v[80:83]
	v_mfma_f32_16x16x32_bf16 v[72:75], v[154:157], v[202:205], v[72:75]
	v_mfma_f32_16x16x32_bf16 v[124:127], v[144:147], v[182:185], v[124:127]
	v_mfma_f32_16x16x32_bf16 v[120:123], v[158:161], v[182:185], v[120:123]
	v_mfma_f32_16x16x32_bf16 v[108:111], v[144:147], v[190:193], v[108:111]
	v_mfma_f32_16x16x32_bf16 v[104:107], v[158:161], v[190:193], v[104:107]
	v_mfma_f32_16x16x32_bf16 v[96:99], v[144:147], v[198:201], v[96:99]
	v_mfma_f32_16x16x32_bf16 v[88:91], v[158:161], v[198:201], v[88:91]
	v_mfma_f32_16x16x32_bf16 v[80:83], v[144:147], v[206:209], v[80:83]
	v_mfma_f32_16x16x32_bf16 v[72:75], v[158:161], v[206:209], v[72:75]
	s_setprio 0
	s_setprio 1
	v_mfma_f32_16x16x32_bf16 v[116:119], v[162:165], v[178:181], v[116:119]
	v_mfma_f32_16x16x32_bf16 v[112:115], v[170:173], v[178:181], v[112:115]
	v_mfma_f32_16x16x32_bf16 v[100:103], v[162:165], v[186:189], v[100:103]
	v_mfma_f32_16x16x32_bf16 v[92:95], v[170:173], v[186:189], v[92:95]
	v_mfma_f32_16x16x32_bf16 v[84:87], v[162:165], v[194:197], v[84:87]
	v_mfma_f32_16x16x32_bf16 v[76:79], v[170:173], v[194:197], v[76:79]
	v_mfma_f32_16x16x32_bf16 v[68:71], v[162:165], v[202:205], v[68:71]
	v_mfma_f32_16x16x32_bf16 v[64:67], v[170:173], v[202:205], v[64:67]
	v_mfma_f32_16x16x32_bf16 v[116:119], v[166:169], v[182:185], v[116:119]
	v_mfma_f32_16x16x32_bf16 v[112:115], v[174:177], v[182:185], v[112:115]
	v_mfma_f32_16x16x32_bf16 v[100:103], v[166:169], v[190:193], v[100:103]
	v_mfma_f32_16x16x32_bf16 v[92:95], v[174:177], v[190:193], v[92:95]
	v_mfma_f32_16x16x32_bf16 v[84:87], v[166:169], v[198:201], v[84:87]
	v_mfma_f32_16x16x32_bf16 v[76:79], v[174:177], v[198:201], v[76:79]
	v_mfma_f32_16x16x32_bf16 v[68:71], v[166:169], v[206:209], v[68:71]
	v_mfma_f32_16x16x32_bf16 v[64:67], v[174:177], v[206:209], v[64:67]
	s_setprio 0
	s_barrier
	s_add_i32 s2, s44, s33
	s_mov_b32 m0, s2
	ds_read_b128 v[178:181], v153 offset:16384
	ds_read_b128 v[182:185], v153 offset:17408
	ds_read_b128 v[186:189], v153 offset:18432
	ds_read_b128 v[190:193], v153 offset:19456
	ds_read_b128 v[194:197], v153 offset:20480
	ds_read_b128 v[198:201], v153 offset:21504
	ds_read_b128 v[202:205], v153 offset:22528
	ds_read_b128 v[206:209], v153 offset:23552
	global_load_lds_dwordx4 v132, s[28:29]
	s_add_i32 m0, s2, 0x2000
	s_add_u32 s12, s28, 0x100000
	s_addc_u32 s13, s29, 0
	s_add_i32 s2, s45, s33
	global_load_lds_dwordx4 v128, s[28:29]
	s_mov_b32 m0, s2
	s_nop 0
	global_load_lds_dwordx4 v132, s[12:13]
	s_add_i32 m0, s2, 0x2000
	s_nop 0
	global_load_lds_dwordx4 v128, s[12:13]
	s_mov_b32 m0, s25
	s_nop 0
	global_load_lds_dwordx4 v134, s[30:31]
	s_mov_b32 m0, s38
	s_nop 0
	global_load_lds_dwordx4 v130, s[30:31]
	s_waitcnt vmcnt(8)
	s_waitcnt lgkmcnt(0)
	s_barrier
; #define PG8_STAGE(bufoff, gbase, voff) do { _Pragma("unroll") for (int _i = 0; _i < 2; ++_i) \
;         __builtin_amdgcn_global_load_lds((const unsigned*)((const char*)(gbase) + (voff)[_i]), (LAS unsigned*)(lds + (bufoff) + ldsw + _i * 8192), 16, 0, 0); } while (0)
; #define PG8_LDA(dst, b, h) do { _Pragma("unroll") for (int m = 0; m < 4; ++m) _Pragma("unroll") for (int k = 0; k < 2; ++k) dst[m][k] = *(const LAS bf16x8*)(lds + PG8_SA(b, h) + aoff + m * 2048 + k * 1024); } while (0)
; #define PG8_LDB(dst, b, h) do { _Pragma("unroll") for (int n = 0; n < 2; ++n) _Pragma("unroll") for (int k = 0; k < 2; ++k) dst[n][k] = *(const LAS bf16x8*)(lds + PG8_SB(b, h) + boff + n * 2048 + k * 1024); } while (0)
; #define PG8_MMA(ai, bj, At, Bt) do { __builtin_amdgcn_s_setprio(1); _Pragma("unroll") for (int m = 0; m < 4; ++m) _Pragma("unroll") for (int n = 0; n < 2; ++n) _Pragma("unroll") for (int k = 0; k < 2; ++k) \
;         acc[ai][bj][m][n] = __builtin_amdgcn_mfma_f32_16x16x32_bf16(Bt[n][k], At[m][k], acc[ai][bj][m][n], 0, 0, 0); __builtin_amdgcn_s_setprio(0); } while (0)
; #define PG8_WAIT_V(n) asm volatile("s_waitcnt vmcnt(" #n ")" ::: "memory")
; #define PG8_WAIT_L(n) asm volatile("s_waitcnt lgkmcnt(" #n ")" ::: "memory")
; #define PG8_BAR __builtin_amdgcn_s_barrier()
; #define PG8_SCHED __builtin_amdgcn_sched_barrier(0)
; template <class Epi, bool ALIGN_EPI, bool SPLITA>
; __device__ __forceinline__ void gemm_phase(LAS unsigned char* lds, const Gemm g, const StaticOrder& S, const Epi& E) {
;     ...
;             PG8_WAIT_V(8); PG8_WAIT_L(0); PG8_BAR; PG8_MMA(1, 0, At, B0); PG8_MMA(1, 1, At, B1); PG8_BAR; PG8_SCHED;
;             PG8_LDB(B0, 1, 0); PG8_LDB(B1, 1, 1); PG8_SCHED; PG8_LDA(At, 1, 0); PG8_STAGE(PG8_SA(0, 1), a2h, vo2);
;             PG8_WAIT_V(8); PG8_WAIT_L(0); PG8_BAR; PG8_MMA(0, 0, At, B0); PG8_MMA(0, 1, At, B1); PG8_BAR; PG8_SCHED;
	s_setprio 1
	s_waitcnt lgkmcnt(0)
	v_mfma_f32_16x16x32_bf16 v[60:63], v[140:143], v[178:181], v[60:63]
	v_mfma_f32_16x16x32_bf16 v[56:59], v[154:157], v[178:181], v[56:59]
	v_mfma_f32_16x16x32_bf16 v[40:43], v[140:143], v[186:189], v[40:43]
	v_mfma_f32_16x16x32_bf16 v[32:35], v[154:157], v[186:189], v[32:35]
	v_mfma_f32_16x16x32_bf16 v[20:23], v[140:143], v[194:197], v[20:23]
	v_mfma_f32_16x16x32_bf16 v[8:11], v[154:157], v[194:197], v[8:11]
	v_mfma_f32_16x16x32_bf16 v[4:7], v[140:143], v[202:205], v[4:7]
	v_mfma_f32_16x16x32_bf16 v[0:3], v[154:157], v[202:205], v[0:3]
	v_mfma_f32_16x16x32_bf16 v[60:63], v[144:147], v[182:185], v[60:63]
	v_mfma_f32_16x16x32_bf16 v[56:59], v[158:161], v[182:185], v[56:59]
	v_mfma_f32_16x16x32_bf16 v[40:43], v[144:147], v[190:193], v[40:43]
	v_mfma_f32_16x16x32_bf16 v[32:35], v[158:161], v[190:193], v[32:35]
	v_mfma_f32_16x16x32_bf16 v[20:23], v[144:147], v[198:201], v[20:23]
	v_mfma_f32_16x16x32_bf16 v[8:11], v[158:161], v[198:201], v[8:11]
	v_mfma_f32_16x16x32_bf16 v[4:7], v[144:147], v[206:209], v[4:7]
	v_mfma_f32_16x16x32_bf16 v[0:3], v[158:161], v[206:209], v[0:3]
	s_setprio 0
	s_setprio 1
	v_mfma_f32_16x16x32_bf16 v[44:47], v[162:165], v[178:181], v[44:47]
	v_mfma_f32_16x16x32_bf16 v[36:39], v[170:173], v[178:181], v[36:39]
	v_mfma_f32_16x16x32_bf16 v[52:55], v[162:165], v[186:189], v[52:55]
	v_mfma_f32_16x16x32_bf16 v[48:51], v[170:173], v[186:189], v[48:51]
	v_mfma_f32_16x16x32_bf16 v[28:31], v[162:165], v[194:197], v[28:31]
	v_mfma_f32_16x16x32_bf16 v[24:27], v[170:173], v[194:197], v[24:27]
	v_mfma_f32_16x16x32_bf16 v[16:19], v[162:165], v[202:205], v[16:19]
	v_mfma_f32_16x16x32_bf16 v[12:15], v[170:173], v[202:205], v[12:15]
	v_mfma_f32_16x16x32_bf16 v[44:47], v[166:169], v[182:185], v[44:47]
	v_mfma_f32_16x16x32_bf16 v[36:39], v[174:177], v[182:185], v[36:39]
	v_mfma_f32_16x16x32_bf16 v[52:55], v[166:169], v[190:193], v[52:55]
	v_mfma_f32_16x16x32_bf16 v[48:51], v[174:177], v[190:193], v[48:51]
	v_mfma_f32_16x16x32_bf16 v[28:31], v[166:169], v[198:201], v[28:31]
	v_mfma_f32_16x16x32_bf16 v[24:27], v[174:177], v[198:201], v[24:27]
	v_mfma_f32_16x16x32_bf16 v[16:19], v[166:169], v[206:209], v[16:19]
	v_mfma_f32_16x16x32_bf16 v[12:15], v[174:177], v[206:209], v[12:15]
	s_setprio 0
	s_barrier
	s_add_i32 s2, 0, 0x18000
	s_add_i32 s54, 0, 0x1c000
	v_add_u32_e32 v158, s2, v149
	v_add_u32_e32 v174, s54, v149
	ds_read_b128 v[140:143], v158
	ds_read_b128 v[144:147], v158 offset:1024
	ds_read_b128 v[154:157], v158 offset:2048
	ds_read_b128 v[158:161], v158 offset:3072
	ds_read_b128 v[162:165], v174
	ds_read_b128 v[166:169], v174 offset:1024
	ds_read_b128 v[170:173], v174 offset:2048
	ds_read_b128 v[174:177], v174 offset:3072
	s_add_u32 s12, s30, 0x10000
	s_addc_u32 s13, s31, 0
	s_mov_b32 m0, s39
	ds_read_b128 v[178:181], v153 offset:32768
	ds_read_b128 v[182:185], v153 offset:33792
	ds_read_b128 v[186:189], v153 offset:34816
	ds_read_b128 v[190:193], v153 offset:35840
	ds_read_b128 v[194:197], v153 offset:36864
	ds_read_b128 v[198:201], v153 offset:37888
	ds_read_b128 v[202:205], v153 offset:38912
	ds_read_b128 v[206:209], v153 offset:39936
	global_load_lds_dwordx4 v134, s[12:13]
	s_mov_b32 m0, s40
	s_nop 0
	global_load_lds_dwordx4 v130, s[12:13]
	s_waitcnt vmcnt(8)
	s_waitcnt lgkmcnt(0)
	s_barrier
	s_setprio 1
	s_waitcnt lgkmcnt(0)
	v_mfma_f32_16x16x32_bf16 v[124:127], v[140:143], v[178:181], v[124:127]
	v_mfma_f32_16x16x32_bf16 v[120:123], v[154:157], v[178:181], v[120:123]
	v_mfma_f32_16x16x32_bf16 v[108:111], v[140:143], v[186:189], v[108:111]
	v_mfma_f32_16x16x32_bf16 v[104:107], v[154:157], v[186:189], v[104:107]
	v_mfma_f32_16x16x32_bf16 v[96:99], v[140:143], v[194:197], v[96:99]
	v_mfma_f32_16x16x32_bf16 v[88:91], v[154:157], v[194:197], v[88:91]
	v_mfma_f32_16x16x32_bf16 v[80:83], v[140:143], v[202:205], v[80:83]
	v_mfma_f32_16x16x32_bf16 v[72:75], v[154:157], v[202:205], v[72:75]
	v_mfma_f32_16x16x32_bf16 v[124:127], v[144:147], v[182:185], v[124:127]
	v_mfma_f32_16x16x32_bf16 v[120:123], v[158:161], v[182:185], v[120:123]
	v_mfma_f32_16x16x32_bf16 v[108:111], v[144:147], v[190:193], v[108:111]
	v_mfma_f32_16x16x32_bf16 v[104:107], v[158:161], v[190:193], v[104:107]
	v_mfma_f32_16x16x32_bf16 v[96:99], v[144:147], v[198:201], v[96:99]
	v_mfma_f32_16x16x32_bf16 v[88:91], v[158:161], v[198:201], v[88:91]
	v_mfma_f32_16x16x32_bf16 v[80:83], v[144:147], v[206:209], v[80:83]
	v_mfma_f32_16x16x32_bf16 v[72:75], v[158:161], v[206:209], v[72:75]
	s_setprio 0
	s_setprio 1
	v_mfma_f32_16x16x32_bf16 v[116:119], v[162:165], v[178:181], v[116:119]
	v_mfma_f32_16x16x32_bf16 v[112:115], v[170:173], v[178:181], v[112:115]
	v_mfma_f32_16x16x32_bf16 v[100:103], v[162:165], v[186:189], v[100:103]
	v_mfma_f32_16x16x32_bf16 v[92:95], v[170:173], v[186:189], v[92:95]
	v_mfma_f32_16x16x32_bf16 v[84:87], v[162:165], v[194:197], v[84:87]
	v_mfma_f32_16x16x32_bf16 v[76:79], v[170:173], v[194:197], v[76:79]
	v_mfma_f32_16x16x32_bf16 v[68:71], v[162:165], v[202:205], v[68:71]
	v_mfma_f32_16x16x32_bf16 v[64:67], v[170:173], v[202:205], v[64:67]
	v_mfma_f32_16x16x32_bf16 v[116:119], v[166:169], v[182:185], v[116:119]
	v_mfma_f32_16x16x32_bf16 v[112:115], v[174:177], v[182:185], v[112:115]
	v_mfma_f32_16x16x32_bf16 v[100:103], v[166:169], v[190:193], v[100:103]
	v_mfma_f32_16x16x32_bf16 v[92:95], v[174:177], v[190:193], v[92:95]
	v_mfma_f32_16x16x32_bf16 v[84:87], v[166:169], v[198:201], v[84:87]
	v_mfma_f32_16x16x32_bf16 v[76:79], v[174:177], v[198:201], v[76:79]
	v_mfma_f32_16x16x32_bf16 v[68:71], v[166:169], v[206:209], v[68:71]
	v_mfma_f32_16x16x32_bf16 v[64:67], v[174:177], v[206:209], v[64:67]
	s_setprio 0
	s_barrier
; #define PG8_STAGE(bufoff, gbase, voff) do { _Pragma("unroll") for (int _i = 0; _i < 2; ++_i) \
;         __builtin_amdgcn_global_load_lds((const unsigned*)((const char*)(gbase) + (voff)[_i]), (LAS unsigned*)(lds + (bufoff) + ldsw + _i * 8192), 16, 0, 0); } while (0)
; #define PG8_LDA(dst, b, h) do { _Pragma("unroll") for (int m = 0; m < 4; ++m) _Pragma("unroll") for (int k = 0; k < 2; ++k) dst[m][k] = *(const LAS bf16x8*)(lds + PG8_SA(b, h) + aoff + m * 2048 + k * 1024); } while (0)
; #define PG8_MMA(ai, bj, At, Bt) do { __builtin_amdgcn_s_setprio(1); _Pragma("unroll") for (int m = 0; m < 4; ++m) _Pragma("unroll") for (int n = 0; n < 2; ++n) _Pragma("unroll") for (int k = 0; k < 2; ++k) \
;         acc[ai][bj][m][n] = __builtin_amdgcn_mfma_f32_16x16x32_bf16(Bt[n][k], At[m][k], acc[ai][bj][m][n], 0, 0, 0); __builtin_amdgcn_s_setprio(0); } while (0)
; #define PG8_WAIT_V(n) asm volatile("s_waitcnt vmcnt(" #n ")" ::: "memory")
; #define PG8_WAIT_L(n) asm volatile("s_waitcnt lgkmcnt(" #n ")" ::: "memory")
; #define PG8_BAR __builtin_amdgcn_s_barrier()
; #define PG8_SCHED __builtin_amdgcn_sched_barrier(0)
; template <class Epi, bool ALIGN_EPI, bool SPLITA>
; __device__ __forceinline__ void gemm_phase(LAS unsigned char* lds, const Gemm g, const StaticOrder& S, const Epi& E) {
;     ...
;             PG8_WAIT_V(8); PG8_WAIT_L(0); PG8_BAR; PG8_MMA(0, 0, At, B0); PG8_MMA(0, 1, At, B1); PG8_BAR; PG8_SCHED;
;             PG8_LDA(At, 1, 1); PG8_STAGE(PG8_SB(1, 0), b3, voffB); PG8_STAGE(PG8_SB(1, 1), b3 + hstepB, voffB); PG8_STAGE(PG8_SA(1, 0), a3, vo2);
;             PG8_WAIT_V(8); PG8_WAIT_L(0); PG8_BAR; PG8_MMA(1, 0, At, B0); PG8_MMA(1, 1, At, B1); PG8_BAR; PG8_SCHED;
;         }
	s_add_i32 s2, s2, s33
	s_add_u32 s98, s28, s6
	s_addc_u32 s99, s29, s7
	s_add_u32 s100, s30, 0x800
	s_addc_u32 s101, s31, 0
	s_mov_b32 m0, s2
	ds_read_b128 v[178:181], v153 offset:49152
	ds_read_b128 v[182:185], v153 offset:50176
	ds_read_b128 v[186:189], v153 offset:51200
	ds_read_b128 v[190:193], v153 offset:52224
	ds_read_b128 v[194:197], v153 offset:53248
	ds_read_b128 v[198:201], v153 offset:54272
	ds_read_b128 v[202:205], v153 offset:55296
	ds_read_b128 v[206:209], v153 offset:56320
	global_load_lds_dwordx4 v132, s[98:99]
	s_add_i32 m0, s2, 0x2000
	s_add_u32 s12, s28, 0x100080
	s_addc_u32 s13, s29, 0
	s_add_i32 s2, s54, s33
	global_load_lds_dwordx4 v128, s[98:99]
	s_mov_b32 m0, s2
	s_nop 0
	global_load_lds_dwordx4 v132, s[12:13]
	s_add_i32 m0, s2, 0x2000
	s_nop 0
	global_load_lds_dwordx4 v128, s[12:13]
	s_mov_b32 m0, s41
	s_nop 0
	global_load_lds_dwordx4 v134, s[100:101]
	s_mov_b32 m0, s42
	s_nop 0
	global_load_lds_dwordx4 v130, s[100:101]
	s_waitcnt vmcnt(8)
	s_waitcnt lgkmcnt(0)
	s_barrier
	s_setprio 1
	s_waitcnt lgkmcnt(0)
	v_mfma_f32_16x16x32_bf16 v[60:63], v[140:143], v[178:181], v[60:63]
	v_mfma_f32_16x16x32_bf16 v[56:59], v[154:157], v[178:181], v[56:59]
	v_mfma_f32_16x16x32_bf16 v[40:43], v[140:143], v[186:189], v[40:43]
	v_mfma_f32_16x16x32_bf16 v[32:35], v[154:157], v[186:189], v[32:35]
	v_mfma_f32_16x16x32_bf16 v[20:23], v[140:143], v[194:197], v[20:23]
	v_mfma_f32_16x16x32_bf16 v[8:11], v[154:157], v[194:197], v[8:11]
	v_mfma_f32_16x16x32_bf16 v[4:7], v[140:143], v[202:205], v[4:7]
	v_mfma_f32_16x16x32_bf16 v[0:3], v[154:157], v[202:205], v[0:3]
	v_mfma_f32_16x16x32_bf16 v[60:63], v[144:147], v[182:185], v[60:63]
	v_mfma_f32_16x16x32_bf16 v[56:59], v[158:161], v[182:185], v[56:59]
	v_mfma_f32_16x16x32_bf16 v[40:43], v[144:147], v[190:193], v[40:43]
	v_mfma_f32_16x16x32_bf16 v[32:35], v[158:161], v[190:193], v[32:35]
	v_mfma_f32_16x16x32_bf16 v[20:23], v[144:147], v[198:201], v[20:23]
	v_mfma_f32_16x16x32_bf16 v[8:11], v[158:161], v[198:201], v[8:11]
	v_mfma_f32_16x16x32_bf16 v[4:7], v[144:147], v[206:209], v[4:7]
	v_mfma_f32_16x16x32_bf16 v[0:3], v[158:161], v[206:209], v[0:3]
	s_setprio 0
	s_setprio 1
	v_mfma_f32_16x16x32_bf16 v[44:47], v[162:165], v[178:181], v[44:47]
	v_mfma_f32_16x16x32_bf16 v[36:39], v[170:173], v[178:181], v[36:39]
	v_mfma_f32_16x16x32_bf16 v[52:55], v[162:165], v[186:189], v[52:55]
	v_mfma_f32_16x16x32_bf16 v[48:51], v[170:173], v[186:189], v[48:51]
	v_mfma_f32_16x16x32_bf16 v[28:31], v[162:165], v[194:197], v[28:31]
	v_mfma_f32_16x16x32_bf16 v[24:27], v[170:173], v[194:197], v[24:27]
	v_mfma_f32_16x16x32_bf16 v[16:19], v[162:165], v[202:205], v[16:19]
	v_mfma_f32_16x16x32_bf16 v[12:15], v[170:173], v[202:205], v[12:15]
	v_mfma_f32_16x16x32_bf16 v[44:47], v[166:169], v[182:185], v[44:47]
	v_mfma_f32_16x16x32_bf16 v[36:39], v[174:177], v[182:185], v[36:39]
	v_mfma_f32_16x16x32_bf16 v[52:55], v[166:169], v[190:193], v[52:55]
	v_mfma_f32_16x16x32_bf16 v[48:51], v[174:177], v[190:193], v[48:51]
	v_mfma_f32_16x16x32_bf16 v[28:31], v[166:169], v[198:201], v[28:31]
	v_mfma_f32_16x16x32_bf16 v[24:27], v[174:177], v[198:201], v[24:27]
	v_mfma_f32_16x16x32_bf16 v[16:19], v[166:169], v[206:209], v[16:19]
	v_mfma_f32_16x16x32_bf16 v[12:15], v[174:177], v[206:209], v[12:15]
	s_setprio 0
	s_barrier
	s_add_u32 s50, s50, 0x100
	s_addc_u32 s51, s51, 0
	s_addk_i32 s52, 0x1000
	s_cmp_gt_u32 s53, 61
	s_mov_b32 s28, s53
	s_cbranch_scc0 .LBB0_867
	s_and_b64 vcc, exec, s[10:11]
	s_cbranch_vccz .LBB0_870
	s_barrier
